# first-iteration vmcnt relaxed to 16 in the peeled k-tile-0 code (epilogue stores stay in flight) + G1 epilogue/header waits counted
# speedup vs baseline: 1.0234x; 1.0028x over previous
; #define PG8_STAGE(bufoff, gbase, voff) do { _Pragma("unroll") for (int _i = 0; _i < 2; ++_i) \
;         __builtin_amdgcn_global_load_lds((const unsigned*)((const char*)(gbase) + (voff)[_i]), (PG8_LAS unsigned*)(lds + (bufoff) + ldsw + _i * 8192), 16, 0, 0); } while (0)
; #define PG8_LDA(dst, b, h) do { _Pragma("unroll") for (int m = 0; m < 4; ++m) _Pragma("unroll") for (int k = 0; k < 2; ++k) dst[m][k] = *(const PG8_LAS bf16x8*)(lds + PG8_SA(b, h) + aoff + m * 2048 + k * 1024); } while (0)
; #define PG8_LDB(dst, b, h) do { _Pragma("unroll") for (int n = 0; n < 2; ++n) _Pragma("unroll") for (int k = 0; k < 2; ++k) dst[n][k] = *(const PG8_LAS bf16x8*)(lds + PG8_SB(b, h) + boff + n * 2048 + k * 1024); } while (0)
; #define PG8_MMA(ai, bj, At, Bt) do { __builtin_amdgcn_s_setprio(1); _Pragma("unroll") for (int m = 0; m < 4; ++m) _Pragma("unroll") for (int n = 0; n < 2; ++n) _Pragma("unroll") for (int k = 0; k < 2; ++k) \
;         acc[ai][bj][m][n] = __builtin_amdgcn_mfma_f32_16x16x32_bf16(Bt[n][k], At[m][k], acc[ai][bj][m][n], 0, 0, 0); __builtin_amdgcn_s_setprio(0); } while (0)
; #define PG8_WAIT_V(n) asm volatile("s_waitcnt vmcnt(" #n ")" ::: "memory")
; #define PG8_WAIT_L(n) asm volatile("s_waitcnt lgkmcnt(" #n ")" ::: "memory")
; #define PG8_BAR __builtin_amdgcn_s_barrier()
; #define PG8_SCHED __builtin_amdgcn_sched_barrier(0)
; template <class Epi, class Sched>
; __device__ __forceinline__ void gemm_phase(PG8_LAS unsigned char* lds, const Gemm g, const Sched& S, const Epi& E) {
;     ...
;         const bool has_next = S.next(ui + 1, nxt);
;         const char* nA = has_next ? (const char*)g.A + (size_t)nxt.pm * tstepA : cA; const char* nB = has_next ? (const char*)g.Bt + (size_t)nxt.pn * tstepB : cB;
;         for (int t = 0; t < nt; t += 2) {
;             const bool last = (t == nt - 2);
;             const char* a1 = cA + (size_t)(t + 1) * kstep;
;             const char* a2 = last ? nA : cA + (size_t)(t + 2) * kstep; const char* b2 = last ? nB : cB + (size_t)(t + 2) * kstep;
;             const char* a3 = a2 + kstep; const char* b3 = b2 + kstep;
;             PG8_LDB(B0, 0, 0); PG8_LDB(B1, 0, 1); PG8_SCHED; PG8_LDA(At, 0, 0); PG8_STAGE(PG8_SA(1, 1), a1 + hstepA, voffA);
;             PG8_WAIT_V(8); PG8_WAIT_L(0); PG8_BAR; PG8_MMA(0, 0, At, B0); PG8_MMA(0, 1, At, B1); PG8_BAR; PG8_SCHED;
.LBB0_161:
	s_ashr_i32 s17, s16, 31
	s_lshl_b64 s[18:19], s[16:17], 19
	s_add_u32 s18, s36, s18
	s_addc_u32 s19, s37, s19
	s_and_b64 s[20:21], s[4:5], exec
	s_cselect_b32 s33, s19, s23
	s_cselect_b32 s61, s18, s22
	s_ashr_i32 s15, s14, 31
	s_lshl_b64 s[20:21], s[14:15], 19
	v_readlane_b32 s15, v254, 56
	s_add_u32 s20, s15, s20
	v_readlane_b32 s15, v254, 57
	s_addc_u32 s21, s15, s21
	s_and_b64 s[26:27], s[4:5], exec
	s_cselect_b32 s15, s21, s25
	s_cselect_b32 s70, s20, s24
	s_add_u32 s22, s22, 0x40080
	s_addc_u32 s23, s23, 0
	s_add_u32 s71, s24, 0x100
	v_mov_b32_e32 v2, 0
	s_addc_u32 s75, s25, 0
	s_mov_b32 s64, -2
	s_add_u32 s24, s22, 0xfffc0080
	s_addc_u32 s25, s23, -1
	s_add_i32 s65, 0, 0x10000
	s_cmp_eq_u32 s64, 12
	s_cselect_b32 s27, s33, s25
	s_cselect_b32 s26, s61, s24
	v_add_u32_e32 v151, s65, v166
	s_cselect_b32 s25, s15, s75
	s_cselect_b32 s24, s70, s71
	s_add_i32 s74, 0, 0x14000
	ds_read_b128 v[122:125], v151
	s_waitcnt lgkmcnt(0)
	ds_read_b128 v[152:155], v151 offset:1024
	ds_read_b128 v[156:159], v151 offset:2048
	ds_read_b128 v[160:163], v151 offset:3072
	v_add_u32_e32 v151, s74, v166
	ds_read_b128 v[172:175], v151
	ds_read_b128 v[176:179], v151 offset:1024
	ds_read_b128 v[180:183], v151 offset:2048
	ds_read_b128 v[184:187], v151 offset:3072
	v_lshl_add_u64 v[164:165], s[22:23], 0, v[146:147]
	s_add_i32 m0, s29, 0xc000
	ds_read_b128 v[188:191], v171
	ds_read_b128 v[192:195], v171 offset:1024
	ds_read_b128 v[196:199], v171 offset:2048
	ds_read_b128 v[200:203], v171 offset:3072
	ds_read_b128 v[204:207], v171 offset:4096
	ds_read_b128 v[214:217], v171 offset:5120
	ds_read_b128 v[218:221], v171 offset:6144
	ds_read_b128 v[222:225], v171 offset:7168
	global_load_lds_dwordx4 v[164:165], off
	v_lshl_add_u64 v[164:165], s[22:23], 0, v[148:149]
	s_add_i32 m0, s29, 0xe000
	s_nop 0
	global_load_lds_dwordx4 v[164:165], off
	s_waitcnt vmcnt(16)
	s_waitcnt lgkmcnt(0)
	s_barrier
	s_setprio 1
	s_waitcnt lgkmcnt(0)
	v_mfma_f32_16x16x32_bf16 v[130:133], v[122:125], v[188:191], 0
	v_mfma_f32_16x16x32_bf16 v[126:129], v[156:159], v[188:191], 0
	v_mfma_f32_16x16x32_bf16 v[110:113], v[122:125], v[196:199], 0
	v_mfma_f32_16x16x32_bf16 v[106:109], v[156:159], v[196:199], 0
	v_mfma_f32_16x16x32_bf16 v[94:97], v[122:125], v[204:207], 0
	v_mfma_f32_16x16x32_bf16 v[90:93], v[156:159], v[204:207], 0
	v_mfma_f32_16x16x32_bf16 v[78:81], v[122:125], v[218:221], 0
	v_mfma_f32_16x16x32_bf16 v[74:77], v[156:159], v[218:221], 0
	v_mfma_f32_16x16x32_bf16 v[130:133], v[152:155], v[192:195], v[130:133]
	v_mfma_f32_16x16x32_bf16 v[126:129], v[160:163], v[192:195], v[126:129]
	v_mfma_f32_16x16x32_bf16 v[110:113], v[152:155], v[200:203], v[110:113]
	v_mfma_f32_16x16x32_bf16 v[106:109], v[160:163], v[200:203], v[106:109]
	v_mfma_f32_16x16x32_bf16 v[94:97], v[152:155], v[214:217], v[94:97]
	v_mfma_f32_16x16x32_bf16 v[90:93], v[160:163], v[214:217], v[90:93]
	v_mfma_f32_16x16x32_bf16 v[78:81], v[152:155], v[222:225], v[78:81]
	v_mfma_f32_16x16x32_bf16 v[74:77], v[160:163], v[222:225], v[74:77]
	s_setprio 0
	s_setprio 1
	v_mfma_f32_16x16x32_bf16 v[118:121], v[172:175], v[188:191], 0
	v_mfma_f32_16x16x32_bf16 v[114:117], v[180:183], v[188:191], 0
	v_mfma_f32_16x16x32_bf16 v[102:105], v[172:175], v[196:199], 0
	v_mfma_f32_16x16x32_bf16 v[98:101], v[180:183], v[196:199], 0
	v_mfma_f32_16x16x32_bf16 v[86:89], v[172:175], v[204:207], 0
	v_mfma_f32_16x16x32_bf16 v[82:85], v[180:183], v[204:207], 0
	v_mfma_f32_16x16x32_bf16 v[70:73], v[172:175], v[218:221], 0
	v_mfma_f32_16x16x32_bf16 v[66:69], v[180:183], v[218:221], 0
	v_mfma_f32_16x16x32_bf16 v[118:121], v[176:179], v[192:195], v[118:121]
	v_mfma_f32_16x16x32_bf16 v[114:117], v[184:187], v[192:195], v[114:117]
	v_mfma_f32_16x16x32_bf16 v[102:105], v[176:179], v[200:203], v[102:105]
	v_mfma_f32_16x16x32_bf16 v[98:101], v[184:187], v[200:203], v[98:101]
	v_mfma_f32_16x16x32_bf16 v[86:89], v[176:179], v[214:217], v[86:89]
	v_mfma_f32_16x16x32_bf16 v[82:85], v[184:187], v[214:217], v[82:85]
	v_mfma_f32_16x16x32_bf16 v[70:73], v[176:179], v[222:225], v[70:73]
	v_mfma_f32_16x16x32_bf16 v[66:69], v[184:187], v[222:225], v[66:69]
	s_setprio 0
	s_barrier
; #define PG8_STAGE(bufoff, gbase, voff) do { _Pragma("unroll") for (int _i = 0; _i < 2; ++_i) \
;         __builtin_amdgcn_global_load_lds((const unsigned*)((const char*)(gbase) + (voff)[_i]), (PG8_LAS unsigned*)(lds + (bufoff) + ldsw + _i * 8192), 16, 0, 0); } while (0)
; #define PG8_LDA(dst, b, h) do { _Pragma("unroll") for (int m = 0; m < 4; ++m) _Pragma("unroll") for (int k = 0; k < 2; ++k) dst[m][k] = *(const PG8_LAS bf16x8*)(lds + PG8_SA(b, h) + aoff + m * 2048 + k * 1024); } while (0)
; #define PG8_MMA(ai, bj, At, Bt) do { __builtin_amdgcn_s_setprio(1); _Pragma("unroll") for (int m = 0; m < 4; ++m) _Pragma("unroll") for (int n = 0; n < 2; ++n) _Pragma("unroll") for (int k = 0; k < 2; ++k) \
;         acc[ai][bj][m][n] = __builtin_amdgcn_mfma_f32_16x16x32_bf16(Bt[n][k], At[m][k], acc[ai][bj][m][n], 0, 0, 0); __builtin_amdgcn_s_setprio(0); } while (0)
; #define PG8_WAIT_V(n) asm volatile("s_waitcnt vmcnt(" #n ")" ::: "memory")
; #define PG8_WAIT_L(n) asm volatile("s_waitcnt lgkmcnt(" #n ")" ::: "memory")
; #define PG8_BAR __builtin_amdgcn_s_barrier()
; #define PG8_SCHED __builtin_amdgcn_sched_barrier(0)
; template <class Epi, class Sched>
; __device__ __forceinline__ void gemm_phase(PG8_LAS unsigned char* lds, const Gemm g, const Sched& S, const Epi& E) {
;     ...
;             PG8_LDA(At, 0, 1); PG8_STAGE(PG8_SB(0, 0), b2, voffB); PG8_STAGE(PG8_SB(0, 1), b2 + hstepB, voffB); PG8_STAGE(PG8_SA(0, 0), a2, voffA);
;             PG8_WAIT_V(8); PG8_WAIT_L(0); PG8_BAR; PG8_MMA(1, 0, At, B0); PG8_MMA(1, 1, At, B1); PG8_BAR; PG8_SCHED;
	s_add_i32 s65, s65, s28
	v_lshl_add_u64 v[164:165], s[24:25], 0, v[136:137]
	s_mov_b32 m0, s65
	ds_read_b128 v[188:191], v171 offset:16384
	ds_read_b128 v[192:195], v171 offset:17408
	ds_read_b128 v[196:199], v171 offset:18432
	ds_read_b128 v[200:203], v171 offset:19456
	ds_read_b128 v[204:207], v171 offset:20480
	ds_read_b128 v[214:217], v171 offset:21504
	ds_read_b128 v[218:221], v171 offset:22528
	ds_read_b128 v[222:225], v171 offset:23552
	global_load_lds_dwordx4 v[164:165], off
	s_add_i32 m0, s65, 0x2000
	s_add_u32 s66, s24, 0x40000
	v_lshl_add_u64 v[208:209], s[24:25], 0, v[140:141]
	s_addc_u32 s67, s25, 0
	s_add_i32 s65, s74, s28
	global_load_lds_dwordx4 v[208:209], off
	v_lshl_add_u64 v[210:211], s[66:67], 0, v[136:137]
	s_mov_b32 m0, s65
	v_lshl_add_u64 v[226:227], s[26:27], 0, v[138:139]
	global_load_lds_dwordx4 v[210:211], off
	v_lshl_add_u64 v[210:211], s[66:67], 0, v[140:141]
	s_add_i32 m0, s65, 0x2000
	s_nop 0
	global_load_lds_dwordx4 v[210:211], off
	v_lshl_add_u64 v[210:211], s[26:27], 0, v[134:135]
	s_mov_b32 m0, s29
	s_nop 0
	global_load_lds_dwordx4 v[210:211], off
	s_mov_b32 m0, s30
	s_nop 0
	global_load_lds_dwordx4 v[226:227], off
	s_waitcnt vmcnt(8)
	s_waitcnt lgkmcnt(0)
	s_barrier
	s_setprio 1
	s_waitcnt lgkmcnt(0)
	v_mfma_f32_16x16x32_bf16 v[62:65], v[122:125], v[188:191], 0
	v_mfma_f32_16x16x32_bf16 v[58:61], v[156:159], v[188:191], 0
	v_mfma_f32_16x16x32_bf16 v[46:49], v[122:125], v[196:199], 0
	v_mfma_f32_16x16x32_bf16 v[42:45], v[156:159], v[196:199], 0
	v_mfma_f32_16x16x32_bf16 v[30:33], v[122:125], v[204:207], 0
	v_mfma_f32_16x16x32_bf16 v[26:29], v[156:159], v[204:207], 0
	v_mfma_f32_16x16x32_bf16 v[14:17], v[122:125], v[218:221], 0
	v_mfma_f32_16x16x32_bf16 v[10:13], v[156:159], v[218:221], 0
	v_mfma_f32_16x16x32_bf16 v[62:65], v[152:155], v[192:195], v[62:65]
	v_mfma_f32_16x16x32_bf16 v[58:61], v[160:163], v[192:195], v[58:61]
	v_mfma_f32_16x16x32_bf16 v[46:49], v[152:155], v[200:203], v[46:49]
	v_mfma_f32_16x16x32_bf16 v[42:45], v[160:163], v[200:203], v[42:45]
	v_mfma_f32_16x16x32_bf16 v[30:33], v[152:155], v[214:217], v[30:33]
	v_mfma_f32_16x16x32_bf16 v[26:29], v[160:163], v[214:217], v[26:29]
	v_mfma_f32_16x16x32_bf16 v[14:17], v[152:155], v[222:225], v[14:17]
	v_mfma_f32_16x16x32_bf16 v[10:13], v[160:163], v[222:225], v[10:13]
	s_setprio 0
	s_setprio 1
	v_mfma_f32_16x16x32_bf16 v[54:57], v[172:175], v[188:191], 0
	v_mfma_f32_16x16x32_bf16 v[50:53], v[180:183], v[188:191], 0
	v_mfma_f32_16x16x32_bf16 v[38:41], v[172:175], v[196:199], 0
	v_mfma_f32_16x16x32_bf16 v[34:37], v[180:183], v[196:199], 0
	v_mfma_f32_16x16x32_bf16 v[22:25], v[172:175], v[204:207], 0
	v_mfma_f32_16x16x32_bf16 v[18:21], v[180:183], v[204:207], 0
	v_mfma_f32_16x16x32_bf16 v[6:9], v[172:175], v[218:221], 0
	v_mfma_f32_16x16x32_bf16 v[2:5], v[180:183], v[218:221], 0
	v_mfma_f32_16x16x32_bf16 v[54:57], v[176:179], v[192:195], v[54:57]
	v_mfma_f32_16x16x32_bf16 v[50:53], v[184:187], v[192:195], v[50:53]
	v_mfma_f32_16x16x32_bf16 v[38:41], v[176:179], v[200:203], v[38:41]
	v_mfma_f32_16x16x32_bf16 v[34:37], v[184:187], v[200:203], v[34:37]
	v_mfma_f32_16x16x32_bf16 v[22:25], v[176:179], v[214:217], v[22:25]
	v_mfma_f32_16x16x32_bf16 v[18:21], v[184:187], v[214:217], v[18:21]
	v_mfma_f32_16x16x32_bf16 v[6:9], v[176:179], v[222:225], v[6:9]
	v_mfma_f32_16x16x32_bf16 v[2:5], v[184:187], v[222:225], v[2:5]
	s_setprio 0
	s_barrier
	s_branch .Lpeel_mid_162

; #define PG8_BAR __builtin_amdgcn_s_barrier()
; #define LAS __attribute__((address_space(3)))
; __device__ __forceinline__ float rstd4(const f32x4 q) { return __builtin_amdgcn_rsqf(((q[0] + q[1]) + (q[2] + q[3])) * (1.0f / DM) + EPS); }
; template <class Epi, class Sched>
; __device__ __forceinline__ void gemm_phase(PG8_LAS unsigned char* lds, const Gemm g, const Sched& S, const Epi& E) {
;     ...
;         if (!has_next) break;
; #pragma unroll
;         for (int a = 0; a < 2; ++a)
; #pragma unroll
;             for (int b = 0; b < 2; ++b)
; #pragma unroll
;                 for (int m = 0; m < 4; ++m)
; #pragma unroll
;                     for (int n = 0; n < 2; ++n) acc[a][b][m][n] = (f32x4){0.f, 0.f, 0.f, 0.f};
;         cur = nxt; cA = nA; cB = nB; ++ui;
;         if (wr == 1) PG8_BAR;
;     __device__ __forceinline__ void operator()(const f32x4 (&acc)[2][2][4][2], const pg8::Unit& u, int wr, int wc, int fr, int fq, LAS unsigned char* lds, int wid, int lane, const pg8::Unit& nxt, bool has_next, int ui) const {
;     ...
;         __builtin_amdgcn_sched_barrier(0);
;         {
;             float rn = rstd4(qn); asm volatile("" : "+v"(rn));
;             if (pre) ((LAS float*)(lds + RS_OFF))[((ui + 1) & 1) * 256 + tid] = rn;
;         }
.LBB0_171:
	s_waitcnt vmcnt(8)
	s_nop 0
	v_add_f32_e32 v2, v122, v123
	v_add_f32_e32 v3, v124, v125
	v_add_f32_e32 v2, v2, v3
	v_fmamk_f32 v2, v2, 0x3a800000, v245
	v_rsq_f32_e32 v2, v2
	s_and_saveexec_b64 s[24:25], s[22:23]
	s_xor_b32 s15, s15, 0x100
	v_lshl_add_u32 v3, s15, 2, v169
	ds_write_b32 v3, v2
	s_or_b64 exec, exec, s[24:25]
	s_andn2_b64 vcc, exec, s[4:5]
	s_mov_b64 s[4:5], -1
	s_cbranch_vccnz .LBB0_158
	s_andn2_b64 vcc, exec, s[10:11]
	s_cbranch_vccnz .LBB0_157
	s_barrier
	s_branch .LBB0_157

; #define PG8_STAGE(bufoff, gbase, voff) do { _Pragma("unroll") for (int _i = 0; _i < 2; ++_i) \
;         __builtin_amdgcn_global_load_lds((const unsigned*)((const char*)(gbase) + (voff)[_i]), (PG8_LAS unsigned*)(lds + (bufoff) + ldsw + _i * 8192), 16, 0, 0); } while (0)
; #define PG8_LDA(dst, b, h) do { _Pragma("unroll") for (int m = 0; m < 4; ++m) _Pragma("unroll") for (int k = 0; k < 2; ++k) dst[m][k] = *(const PG8_LAS bf16x8*)(lds + PG8_SA(b, h) + aoff + m * 2048 + k * 1024); } while (0)
; #define PG8_LDB(dst, b, h) do { _Pragma("unroll") for (int n = 0; n < 2; ++n) _Pragma("unroll") for (int k = 0; k < 2; ++k) dst[n][k] = *(const PG8_LAS bf16x8*)(lds + PG8_SB(b, h) + boff + n * 2048 + k * 1024); } while (0)
; #define PG8_MMA(ai, bj, At, Bt) do { __builtin_amdgcn_s_setprio(1); _Pragma("unroll") for (int m = 0; m < 4; ++m) _Pragma("unroll") for (int n = 0; n < 2; ++n) _Pragma("unroll") for (int k = 0; k < 2; ++k) \
;         acc[ai][bj][m][n] = __builtin_amdgcn_mfma_f32_16x16x32_bf16(Bt[n][k], At[m][k], acc[ai][bj][m][n], 0, 0, 0); __builtin_amdgcn_s_setprio(0); } while (0)
; #define PG8_WAIT_V(n) asm volatile("s_waitcnt vmcnt(" #n ")" ::: "memory")
; #define PG8_WAIT_L(n) asm volatile("s_waitcnt lgkmcnt(" #n ")" ::: "memory")
; #define PG8_BAR __builtin_amdgcn_s_barrier()
; #define PG8_SCHED __builtin_amdgcn_sched_barrier(0)
; template <class Epi, class Sched>
; __device__ __forceinline__ void gemm_phase(PG8_LAS unsigned char* lds, const Gemm g, const Sched& S, const Epi& E) {
;     ...
;         const char* nA = has_next ? (const char*)g.A + (size_t)nxt.pm * tstepA : cA; const char* nB = has_next ? (const char*)g.Bt + (size_t)nxt.pn * tstepB : cB;
;         for (int t = 0; t < nt; t += 2) {
;             const bool last = (t == nt - 2);
;             const char* a1 = cA + (size_t)(t + 1) * kstep;
;             const char* a2 = last ? nA : cA + (size_t)(t + 2) * kstep; const char* b2 = last ? nB : cB + (size_t)(t + 2) * kstep;
;             const char* a3 = a2 + kstep; const char* b3 = b2 + kstep;
;             PG8_LDB(B0, 0, 0); PG8_LDB(B1, 0, 1); PG8_SCHED; PG8_LDA(At, 0, 0); PG8_STAGE(PG8_SA(1, 1), a1 + hstepA, voffA);
;             PG8_WAIT_V(8); PG8_WAIT_L(0); PG8_BAR; PG8_MMA(0, 0, At, B0); PG8_MMA(0, 1, At, B1); PG8_BAR; PG8_SCHED;
.LBB0_255:
	s_and_b64 s[12:13], s[6:7], exec
	s_cselect_b32 vcc_lo, s43, s11
	s_cselect_b32 vcc_hi, s42, s10
	s_add_u32 s74, s10, 0x100
	v_mov_b32_e32 v2, 0
	s_addc_u32 s64, s11, 0
	s_mov_b32 s65, -2
	s_mov_b64 s[10:11], 0
	v_add_u32_e32 v144, s16, v1
	ds_read_b128 v[148:151], v144
	ds_read_b128 v[152:155], v144 offset:1024
	ds_read_b128 v[156:159], v144 offset:2048
	ds_read_b128 v[160:163], v144 offset:3072
	v_add_u32_e32 v144, s17, v1
	s_add_u32 s12, s76, s10
	ds_read_b128 v[164:167], v144
	ds_read_b128 v[168:171], v144 offset:1024
	ds_read_b128 v[172:175], v144 offset:2048
	ds_read_b128 v[176:179], v144 offset:3072
	s_addc_u32 s13, s77, s11
	s_add_u32 s12, s12, 0x2e000100
	s_addc_u32 s13, s13, 0
	s_add_u32 s66, s74, s10
	s_addc_u32 s67, s64, s11
	s_cmpk_eq_i32 s10, 0x500
	s_cselect_b32 s15, s53, s13
	s_cselect_b32 s14, s52, s12
	s_cselect_b32 s13, vcc_lo, s67
	s_cselect_b32 s12, vcc_hi, s66
	v_lshl_add_u64 v[144:145], v[140:141], 0, s[10:11]
	s_add_i32 m0, s48, 0xc000
	ds_read_b128 v[180:183], v147
	ds_read_b128 v[184:187], v147 offset:1024
	ds_read_b128 v[188:191], v147 offset:2048
	ds_read_b128 v[192:195], v147 offset:3072
	ds_read_b128 v[196:199], v147 offset:4096
	ds_read_b128 v[200:203], v147 offset:5120
	ds_read_b128 v[204:207], v147 offset:6144
	ds_read_b128 v[214:217], v147 offset:7168
	global_load_lds_dwordx4 v[144:145], off
	v_lshl_add_u64 v[144:145], v[142:143], 0, s[10:11]
	s_add_i32 m0, s48, 0xe000
	s_nop 0
	global_load_lds_dwordx4 v[144:145], off
	s_waitcnt vmcnt(16)
	s_waitcnt lgkmcnt(0)
	s_barrier
	s_setprio 1
	s_waitcnt lgkmcnt(0)
	v_mfma_f32_16x16x32_bf16 v[126:129], v[148:151], v[180:183], 0
	v_mfma_f32_16x16x32_bf16 v[122:125], v[156:159], v[180:183], 0
	v_mfma_f32_16x16x32_bf16 v[110:113], v[148:151], v[188:191], 0
	v_mfma_f32_16x16x32_bf16 v[106:109], v[156:159], v[188:191], 0
	v_mfma_f32_16x16x32_bf16 v[94:97], v[148:151], v[196:199], 0
	v_mfma_f32_16x16x32_bf16 v[90:93], v[156:159], v[196:199], 0
	v_mfma_f32_16x16x32_bf16 v[78:81], v[148:151], v[204:207], 0
	v_mfma_f32_16x16x32_bf16 v[74:77], v[156:159], v[204:207], 0
	v_mfma_f32_16x16x32_bf16 v[126:129], v[152:155], v[184:187], v[126:129]
	v_mfma_f32_16x16x32_bf16 v[122:125], v[160:163], v[184:187], v[122:125]
	v_mfma_f32_16x16x32_bf16 v[110:113], v[152:155], v[192:195], v[110:113]
	v_mfma_f32_16x16x32_bf16 v[106:109], v[160:163], v[192:195], v[106:109]
	v_mfma_f32_16x16x32_bf16 v[94:97], v[152:155], v[200:203], v[94:97]
	v_mfma_f32_16x16x32_bf16 v[90:93], v[160:163], v[200:203], v[90:93]
	v_mfma_f32_16x16x32_bf16 v[78:81], v[152:155], v[214:217], v[78:81]
	v_mfma_f32_16x16x32_bf16 v[74:77], v[160:163], v[214:217], v[74:77]
	s_setprio 0
	s_setprio 1
	v_mfma_f32_16x16x32_bf16 v[118:121], v[164:167], v[180:183], 0
	v_mfma_f32_16x16x32_bf16 v[114:117], v[172:175], v[180:183], 0
	v_mfma_f32_16x16x32_bf16 v[102:105], v[164:167], v[188:191], 0
	v_mfma_f32_16x16x32_bf16 v[98:101], v[172:175], v[188:191], 0
	v_mfma_f32_16x16x32_bf16 v[86:89], v[164:167], v[196:199], 0
	v_mfma_f32_16x16x32_bf16 v[82:85], v[172:175], v[196:199], 0
	v_mfma_f32_16x16x32_bf16 v[70:73], v[164:167], v[204:207], 0
	v_mfma_f32_16x16x32_bf16 v[66:69], v[172:175], v[204:207], 0
	v_mfma_f32_16x16x32_bf16 v[118:121], v[168:171], v[184:187], v[118:121]
	v_mfma_f32_16x16x32_bf16 v[114:117], v[176:179], v[184:187], v[114:117]
	v_mfma_f32_16x16x32_bf16 v[102:105], v[168:171], v[192:195], v[102:105]
	v_mfma_f32_16x16x32_bf16 v[98:101], v[176:179], v[192:195], v[98:101]
	v_mfma_f32_16x16x32_bf16 v[86:89], v[168:171], v[200:203], v[86:89]
	v_mfma_f32_16x16x32_bf16 v[82:85], v[176:179], v[200:203], v[82:85]
	v_mfma_f32_16x16x32_bf16 v[70:73], v[168:171], v[214:217], v[70:73]
	v_mfma_f32_16x16x32_bf16 v[66:69], v[176:179], v[214:217], v[66:69]
	s_setprio 0
	s_barrier
; #define PG8_STAGE(bufoff, gbase, voff) do { _Pragma("unroll") for (int _i = 0; _i < 2; ++_i) \
;         __builtin_amdgcn_global_load_lds((const unsigned*)((const char*)(gbase) + (voff)[_i]), (PG8_LAS unsigned*)(lds + (bufoff) + ldsw + _i * 8192), 16, 0, 0); } while (0)
; #define PG8_LDA(dst, b, h) do { _Pragma("unroll") for (int m = 0; m < 4; ++m) _Pragma("unroll") for (int k = 0; k < 2; ++k) dst[m][k] = *(const PG8_LAS bf16x8*)(lds + PG8_SA(b, h) + aoff + m * 2048 + k * 1024); } while (0)
; #define PG8_MMA(ai, bj, At, Bt) do { __builtin_amdgcn_s_setprio(1); _Pragma("unroll") for (int m = 0; m < 4; ++m) _Pragma("unroll") for (int n = 0; n < 2; ++n) _Pragma("unroll") for (int k = 0; k < 2; ++k) \
;         acc[ai][bj][m][n] = __builtin_amdgcn_mfma_f32_16x16x32_bf16(Bt[n][k], At[m][k], acc[ai][bj][m][n], 0, 0, 0); __builtin_amdgcn_s_setprio(0); } while (0)
; #define PG8_WAIT_V(n) asm volatile("s_waitcnt vmcnt(" #n ")" ::: "memory")
; #define PG8_WAIT_L(n) asm volatile("s_waitcnt lgkmcnt(" #n ")" ::: "memory")
; #define PG8_BAR __builtin_amdgcn_s_barrier()
; #define PG8_SCHED __builtin_amdgcn_sched_barrier(0)
; template <class Epi, class Sched>
; __device__ __forceinline__ void gemm_phase(PG8_LAS unsigned char* lds, const Gemm g, const Sched& S, const Epi& E) {
;     ...
;             PG8_LDA(At, 0, 1); PG8_STAGE(PG8_SB(0, 0), b2, voffB); PG8_STAGE(PG8_SB(0, 1), b2 + hstepB, voffB); PG8_STAGE(PG8_SA(0, 0), a2, voffA);
;             PG8_WAIT_V(8); PG8_WAIT_L(0); PG8_BAR; PG8_MMA(1, 0, At, B0); PG8_MMA(1, 1, At, B1); PG8_BAR; PG8_SCHED;
	s_add_i32 s66, s16, s59
	v_lshl_add_u64 v[144:145], s[12:13], 0, v[132:133]
	s_mov_b32 m0, s66
	ds_read_b128 v[180:183], v147 offset:16384
	ds_read_b128 v[184:187], v147 offset:17408
	ds_read_b128 v[188:191], v147 offset:18432
	ds_read_b128 v[192:195], v147 offset:19456
	ds_read_b128 v[196:199], v147 offset:20480
	ds_read_b128 v[200:203], v147 offset:21504
	ds_read_b128 v[204:207], v147 offset:22528
	ds_read_b128 v[214:217], v147 offset:23552
	global_load_lds_dwordx4 v[144:145], off
	s_add_i32 m0, s66, 0x2000
	s_add_u32 s66, s12, 0x30000
	v_lshl_add_u64 v[208:209], s[12:13], 0, v[136:137]
	s_addc_u32 s67, s13, 0
	s_add_i32 s82, s17, s59
	global_load_lds_dwordx4 v[208:209], off
	v_lshl_add_u64 v[210:211], s[66:67], 0, v[132:133]
	s_mov_b32 m0, s82
	v_lshl_add_u64 v[218:219], s[14:15], 0, v[134:135]
	global_load_lds_dwordx4 v[210:211], off
	v_lshl_add_u64 v[210:211], s[66:67], 0, v[136:137]
	s_add_i32 m0, s82, 0x2000
	s_nop 0
	global_load_lds_dwordx4 v[210:211], off
	v_lshl_add_u64 v[210:211], s[14:15], 0, v[130:131]
	s_mov_b32 m0, s48
	s_nop 0
	global_load_lds_dwordx4 v[210:211], off
	s_mov_b32 m0, s49
	s_nop 0
	global_load_lds_dwordx4 v[218:219], off
	s_waitcnt vmcnt(8)
	s_waitcnt lgkmcnt(0)
	s_barrier
	s_setprio 1
	s_waitcnt lgkmcnt(0)
	v_mfma_f32_16x16x32_bf16 v[62:65], v[148:151], v[180:183], 0
	v_mfma_f32_16x16x32_bf16 v[58:61], v[156:159], v[180:183], 0
	v_mfma_f32_16x16x32_bf16 v[46:49], v[148:151], v[188:191], 0
	v_mfma_f32_16x16x32_bf16 v[42:45], v[156:159], v[188:191], 0
	v_mfma_f32_16x16x32_bf16 v[30:33], v[148:151], v[196:199], 0
	v_mfma_f32_16x16x32_bf16 v[26:29], v[156:159], v[196:199], 0
	v_mfma_f32_16x16x32_bf16 v[14:17], v[148:151], v[204:207], 0
	v_mfma_f32_16x16x32_bf16 v[10:13], v[156:159], v[204:207], 0
	v_mfma_f32_16x16x32_bf16 v[62:65], v[152:155], v[184:187], v[62:65]
	v_mfma_f32_16x16x32_bf16 v[58:61], v[160:163], v[184:187], v[58:61]
	v_mfma_f32_16x16x32_bf16 v[46:49], v[152:155], v[192:195], v[46:49]
	v_mfma_f32_16x16x32_bf16 v[42:45], v[160:163], v[192:195], v[42:45]
	v_mfma_f32_16x16x32_bf16 v[30:33], v[152:155], v[200:203], v[30:33]
	v_mfma_f32_16x16x32_bf16 v[26:29], v[160:163], v[200:203], v[26:29]
	v_mfma_f32_16x16x32_bf16 v[14:17], v[152:155], v[214:217], v[14:17]
	v_mfma_f32_16x16x32_bf16 v[10:13], v[160:163], v[214:217], v[10:13]
	s_setprio 0
	s_setprio 1
	v_mfma_f32_16x16x32_bf16 v[54:57], v[164:167], v[180:183], 0
	v_mfma_f32_16x16x32_bf16 v[50:53], v[172:175], v[180:183], 0
	v_mfma_f32_16x16x32_bf16 v[38:41], v[164:167], v[188:191], 0
	v_mfma_f32_16x16x32_bf16 v[34:37], v[172:175], v[188:191], 0
	v_mfma_f32_16x16x32_bf16 v[22:25], v[164:167], v[196:199], 0
	v_mfma_f32_16x16x32_bf16 v[18:21], v[172:175], v[196:199], 0
	v_mfma_f32_16x16x32_bf16 v[6:9], v[164:167], v[204:207], 0
	v_mfma_f32_16x16x32_bf16 v[2:5], v[172:175], v[204:207], 0
	v_mfma_f32_16x16x32_bf16 v[54:57], v[168:171], v[184:187], v[54:57]
	v_mfma_f32_16x16x32_bf16 v[50:53], v[176:179], v[184:187], v[50:53]
	v_mfma_f32_16x16x32_bf16 v[38:41], v[168:171], v[192:195], v[38:41]
	v_mfma_f32_16x16x32_bf16 v[34:37], v[176:179], v[192:195], v[34:37]
	v_mfma_f32_16x16x32_bf16 v[22:25], v[168:171], v[200:203], v[22:25]
	v_mfma_f32_16x16x32_bf16 v[18:21], v[176:179], v[200:203], v[18:21]
	v_mfma_f32_16x16x32_bf16 v[6:9], v[168:171], v[214:217], v[6:9]
	v_mfma_f32_16x16x32_bf16 v[2:5], v[176:179], v[214:217], v[2:5]
	s_setprio 0
	s_barrier
	s_branch .Lpeel_mid_256

; #define PG8_STAGE(bufoff, gbase, voff) do { _Pragma("unroll") for (int _i = 0; _i < 2; ++_i) \
;         __builtin_amdgcn_global_load_lds((const unsigned*)((const char*)(gbase) + (voff)[_i]), (PG8_LAS unsigned*)(lds + (bufoff) + ldsw + _i * 8192), 16, 0, 0); } while (0)
; #define PG8_LDA(dst, b, h) do { _Pragma("unroll") for (int m = 0; m < 4; ++m) _Pragma("unroll") for (int k = 0; k < 2; ++k) dst[m][k] = *(const PG8_LAS bf16x8*)(lds + PG8_SA(b, h) + aoff + m * 2048 + k * 1024); } while (0)
; #define PG8_LDB(dst, b, h) do { _Pragma("unroll") for (int n = 0; n < 2; ++n) _Pragma("unroll") for (int k = 0; k < 2; ++k) dst[n][k] = *(const PG8_LAS bf16x8*)(lds + PG8_SB(b, h) + boff + n * 2048 + k * 1024); } while (0)
; #define PG8_MMA(ai, bj, At, Bt) do { __builtin_amdgcn_s_setprio(1); _Pragma("unroll") for (int m = 0; m < 4; ++m) _Pragma("unroll") for (int n = 0; n < 2; ++n) _Pragma("unroll") for (int k = 0; k < 2; ++k) \
;         acc[ai][bj][m][n] = __builtin_amdgcn_mfma_f32_16x16x32_bf16(Bt[n][k], At[m][k], acc[ai][bj][m][n], 0, 0, 0); __builtin_amdgcn_s_setprio(0); } while (0)
; #define PG8_WAIT_V(n) asm volatile("s_waitcnt vmcnt(" #n ")" ::: "memory")
; #define PG8_WAIT_L(n) asm volatile("s_waitcnt lgkmcnt(" #n ")" ::: "memory")
; #define PG8_BAR __builtin_amdgcn_s_barrier()
; #define PG8_SCHED __builtin_amdgcn_sched_barrier(0)
; template <class Epi, class Sched>
; __device__ __forceinline__ void gemm_phase(PG8_LAS unsigned char* lds, const Gemm g, const Sched& S, const Epi& E) {
;     ...
;         const bool has_next = S.next(ui + 1, nxt);
;         const char* nA = has_next ? (const char*)g.A + (size_t)nxt.pm * tstepA : cA; const char* nB = has_next ? (const char*)g.Bt + (size_t)nxt.pn * tstepB : cB;
;         for (int t = 0; t < nt; t += 2) {
;             const bool last = (t == nt - 2);
;             const char* a1 = cA + (size_t)(t + 1) * kstep;
;             const char* a2 = last ? nA : cA + (size_t)(t + 2) * kstep; const char* b2 = last ? nB : cB + (size_t)(t + 2) * kstep;
;             const char* a3 = a2 + kstep; const char* b3 = b2 + kstep;
;             PG8_LDB(B0, 0, 0); PG8_LDB(B1, 0, 1); PG8_SCHED; PG8_LDA(At, 0, 0); PG8_STAGE(PG8_SA(1, 1), a1 + hstepA, voffA);
;             PG8_WAIT_V(8); PG8_WAIT_L(0); PG8_BAR; PG8_MMA(0, 0, At, B0); PG8_MMA(0, 1, At, B1); PG8_BAR; PG8_SCHED;
.LBB0_463:
	s_ashr_i32 s25, s24, 31
	s_lshl_b64 s[26:27], s[24:25], 19
	s_add_u32 s26, s50, s26
	s_addc_u32 s27, s51, s27
	s_and_b64 s[28:29], s[6:7], exec
	s_cselect_b32 s11, s27, s31
	s_cselect_b32 s13, s26, s30
	s_ashr_i32 s23, s22, 31
	s_lshl_b64 s[28:29], s[22:23], 19
	s_add_u32 s28, s61, s28
	s_addc_u32 s29, s85, s29
	s_and_b64 s[46:47], s[6:7], exec
	s_cselect_b32 s21, s29, s71
	s_cselect_b32 s23, s28, s70
	s_add_u32 s30, s30, 0x40080
	s_addc_u32 s31, s31, 0
	s_add_u32 s25, s70, 0x100
	v_mov_b32_e32 v2, 0
	s_addc_u32 s33, s71, 0
	s_mov_b32 s46, -2
	s_add_u32 s47, s30, 0xfffc0080
	s_addc_u32 s48, s31, -1
	s_add_i32 s49, 0, 0x10000
	s_cmp_eq_u32 s46, 12
	s_cselect_b32 s75, s11, s48
	s_cselect_b32 s74, s13, s47
	s_cselect_b32 s71, s21, s33
	s_cselect_b32 s70, s23, s25
	s_add_i32 s47, 0, 0x14000
	v_add_u32_e32 v106, s49, v1
	v_add_u32_e32 v158, s47, v1
	ds_read_b128 v[90:93], v106
	ds_read_b128 v[94:97], v106 offset:1024
	ds_read_b128 v[98:101], v106 offset:2048
	ds_read_b128 v[106:109], v106 offset:3072
	ds_read_b128 v[146:149], v158
	ds_read_b128 v[150:153], v158 offset:1024
	ds_read_b128 v[154:157], v158 offset:2048
	ds_read_b128 v[158:161], v158 offset:3072
	v_lshl_add_u64 v[226:227], s[30:31], 0, v[204:205]
	s_add_i32 m0, s86, 0xc000
	ds_read_b128 v[162:165], v232
	ds_read_b128 v[166:169], v232 offset:1024
	ds_read_b128 v[170:173], v232 offset:2048
	ds_read_b128 v[174:177], v232 offset:3072
	ds_read_b128 v[214:217], v232 offset:4096
	ds_read_b128 v[218:221], v232 offset:5120
	ds_read_b128 v[222:225], v232 offset:6144
	ds_read_b128 v[208:211], v232 offset:7168
	global_load_lds_dwordx4 v[226:227], off
	v_lshl_add_u64 v[226:227], s[30:31], 0, v[206:207]
	s_add_i32 m0, s86, 0xe000
	s_nop 0
	global_load_lds_dwordx4 v[226:227], off
	s_waitcnt vmcnt(16)
	s_waitcnt lgkmcnt(0)
	s_barrier
	s_setprio 1
	s_waitcnt lgkmcnt(0)
	v_mfma_f32_16x16x32_bf16 v[142:145], v[90:93], v[162:165], 0
	v_mfma_f32_16x16x32_bf16 v[138:141], v[98:101], v[162:165], 0
	v_mfma_f32_16x16x32_bf16 v[126:129], v[90:93], v[170:173], 0
	v_mfma_f32_16x16x32_bf16 v[122:125], v[98:101], v[170:173], 0
	v_mfma_f32_16x16x32_bf16 v[110:113], v[90:93], v[214:217], 0
	v_mfma_f32_16x16x32_bf16 v[102:105], v[98:101], v[214:217], 0
	v_mfma_f32_16x16x32_bf16 v[78:81], v[90:93], v[222:225], 0
	v_mfma_f32_16x16x32_bf16 v[74:77], v[98:101], v[222:225], 0
	v_mfma_f32_16x16x32_bf16 v[142:145], v[94:97], v[166:169], v[142:145]
	v_mfma_f32_16x16x32_bf16 v[138:141], v[106:109], v[166:169], v[138:141]
	v_mfma_f32_16x16x32_bf16 v[126:129], v[94:97], v[174:177], v[126:129]
	v_mfma_f32_16x16x32_bf16 v[122:125], v[106:109], v[174:177], v[122:125]
	v_mfma_f32_16x16x32_bf16 v[110:113], v[94:97], v[218:221], v[110:113]
	v_mfma_f32_16x16x32_bf16 v[102:105], v[106:109], v[218:221], v[102:105]
	v_mfma_f32_16x16x32_bf16 v[78:81], v[94:97], v[208:211], v[78:81]
	v_mfma_f32_16x16x32_bf16 v[74:77], v[106:109], v[208:211], v[74:77]
	s_setprio 0
	s_setprio 1
	v_mfma_f32_16x16x32_bf16 v[134:137], v[146:149], v[162:165], 0
	v_mfma_f32_16x16x32_bf16 v[130:133], v[154:157], v[162:165], 0
	v_mfma_f32_16x16x32_bf16 v[118:121], v[146:149], v[170:173], 0
	v_mfma_f32_16x16x32_bf16 v[114:117], v[154:157], v[170:173], 0
	v_mfma_f32_16x16x32_bf16 v[86:89], v[146:149], v[214:217], 0
	v_mfma_f32_16x16x32_bf16 v[82:85], v[154:157], v[214:217], 0
	v_mfma_f32_16x16x32_bf16 v[70:73], v[146:149], v[222:225], 0
	v_mfma_f32_16x16x32_bf16 v[66:69], v[154:157], v[222:225], 0
	v_mfma_f32_16x16x32_bf16 v[134:137], v[150:153], v[166:169], v[134:137]
	v_mfma_f32_16x16x32_bf16 v[130:133], v[158:161], v[166:169], v[130:133]
	v_mfma_f32_16x16x32_bf16 v[118:121], v[150:153], v[174:177], v[118:121]
	v_mfma_f32_16x16x32_bf16 v[114:117], v[158:161], v[174:177], v[114:117]
	v_mfma_f32_16x16x32_bf16 v[86:89], v[150:153], v[218:221], v[86:89]
	v_mfma_f32_16x16x32_bf16 v[82:85], v[158:161], v[218:221], v[82:85]
	v_mfma_f32_16x16x32_bf16 v[70:73], v[150:153], v[208:211], v[70:73]
	v_mfma_f32_16x16x32_bf16 v[66:69], v[158:161], v[208:211], v[66:69]
	s_setprio 0
	s_barrier
; #define PG8_STAGE(bufoff, gbase, voff) do { _Pragma("unroll") for (int _i = 0; _i < 2; ++_i) \
;         __builtin_amdgcn_global_load_lds((const unsigned*)((const char*)(gbase) + (voff)[_i]), (PG8_LAS unsigned*)(lds + (bufoff) + ldsw + _i * 8192), 16, 0, 0); } while (0)
; #define PG8_LDA(dst, b, h) do { _Pragma("unroll") for (int m = 0; m < 4; ++m) _Pragma("unroll") for (int k = 0; k < 2; ++k) dst[m][k] = *(const PG8_LAS bf16x8*)(lds + PG8_SA(b, h) + aoff + m * 2048 + k * 1024); } while (0)
; #define PG8_MMA(ai, bj, At, Bt) do { __builtin_amdgcn_s_setprio(1); _Pragma("unroll") for (int m = 0; m < 4; ++m) _Pragma("unroll") for (int n = 0; n < 2; ++n) _Pragma("unroll") for (int k = 0; k < 2; ++k) \
;         acc[ai][bj][m][n] = __builtin_amdgcn_mfma_f32_16x16x32_bf16(Bt[n][k], At[m][k], acc[ai][bj][m][n], 0, 0, 0); __builtin_amdgcn_s_setprio(0); } while (0)
; #define PG8_WAIT_V(n) asm volatile("s_waitcnt vmcnt(" #n ")" ::: "memory")
; #define PG8_WAIT_L(n) asm volatile("s_waitcnt lgkmcnt(" #n ")" ::: "memory")
; #define PG8_BAR __builtin_amdgcn_s_barrier()
; #define PG8_SCHED __builtin_amdgcn_sched_barrier(0)
; template <class Epi, class Sched>
; __device__ __forceinline__ void gemm_phase(PG8_LAS unsigned char* lds, const Gemm g, const Sched& S, const Epi& E) {
;     ...
;             PG8_LDA(At, 0, 1); PG8_STAGE(PG8_SB(0, 0), b2, voffB); PG8_STAGE(PG8_SB(0, 1), b2 + hstepB, voffB); PG8_STAGE(PG8_SA(0, 0), a2, voffA);
;             PG8_WAIT_V(8); PG8_WAIT_L(0); PG8_BAR; PG8_MMA(1, 0, At, B0); PG8_MMA(1, 1, At, B1); PG8_BAR; PG8_SCHED;
	s_add_i32 s48, s49, s60
	v_lshl_add_u64 v[226:227], s[70:71], 0, v[182:183]
	s_mov_b32 m0, s48
	ds_read_b128 v[162:165], v232 offset:16384
	ds_read_b128 v[166:169], v232 offset:17408
	ds_read_b128 v[170:173], v232 offset:18432
	ds_read_b128 v[174:177], v232 offset:19456
	ds_read_b128 v[208:211], v232 offset:20480
	ds_read_b128 v[214:217], v232 offset:21504
	ds_read_b128 v[218:221], v232 offset:22528
	ds_read_b128 v[222:225], v232 offset:23552
	global_load_lds_dwordx4 v[226:227], off
	s_add_i32 m0, s48, 0x2000
	s_add_u32 s48, s70, 0x40000
	v_lshl_add_u64 v[242:243], s[70:71], 0, v[178:179]
	s_addc_u32 s49, s71, 0
	s_add_i32 s47, s47, s60
	global_load_lds_dwordx4 v[242:243], off
	v_lshl_add_u64 v[250:251], s[48:49], 0, v[182:183]
	s_mov_b32 m0, s47
	v_lshl_add_u64 v[246:247], s[74:75], 0, v[180:181]
	global_load_lds_dwordx4 v[250:251], off
	v_lshl_add_u64 v[250:251], s[48:49], 0, v[178:179]
	s_add_i32 m0, s47, 0x2000
	s_nop 0
	global_load_lds_dwordx4 v[250:251], off
	v_lshl_add_u64 v[250:251], s[74:75], 0, v[184:185]
	s_mov_b32 m0, s86
	s_nop 0
	global_load_lds_dwordx4 v[250:251], off
	s_mov_b32 m0, s87
	s_nop 0
	global_load_lds_dwordx4 v[246:247], off
	s_waitcnt vmcnt(8)
	s_waitcnt lgkmcnt(0)
	s_barrier
	s_setprio 1
	s_waitcnt lgkmcnt(0)
	v_mfma_f32_16x16x32_bf16 v[62:65], v[90:93], v[162:165], 0
	v_mfma_f32_16x16x32_bf16 v[58:61], v[98:101], v[162:165], 0
	v_mfma_f32_16x16x32_bf16 v[46:49], v[90:93], v[170:173], 0
	v_mfma_f32_16x16x32_bf16 v[42:45], v[98:101], v[170:173], 0
	v_mfma_f32_16x16x32_bf16 v[30:33], v[90:93], v[208:211], 0
	v_mfma_f32_16x16x32_bf16 v[26:29], v[98:101], v[208:211], 0
	v_mfma_f32_16x16x32_bf16 v[14:17], v[90:93], v[218:221], 0
	v_mfma_f32_16x16x32_bf16 v[10:13], v[98:101], v[218:221], 0
	v_mfma_f32_16x16x32_bf16 v[62:65], v[94:97], v[166:169], v[62:65]
	v_mfma_f32_16x16x32_bf16 v[58:61], v[106:109], v[166:169], v[58:61]
	v_mfma_f32_16x16x32_bf16 v[46:49], v[94:97], v[174:177], v[46:49]
	v_mfma_f32_16x16x32_bf16 v[42:45], v[106:109], v[174:177], v[42:45]
	v_mfma_f32_16x16x32_bf16 v[30:33], v[94:97], v[214:217], v[30:33]
	v_mfma_f32_16x16x32_bf16 v[26:29], v[106:109], v[214:217], v[26:29]
	v_mfma_f32_16x16x32_bf16 v[14:17], v[94:97], v[222:225], v[14:17]
	v_mfma_f32_16x16x32_bf16 v[10:13], v[106:109], v[222:225], v[10:13]
	s_setprio 0
	s_setprio 1
	v_mfma_f32_16x16x32_bf16 v[54:57], v[146:149], v[162:165], 0
	v_mfma_f32_16x16x32_bf16 v[50:53], v[154:157], v[162:165], 0
	v_mfma_f32_16x16x32_bf16 v[38:41], v[146:149], v[170:173], 0
	v_mfma_f32_16x16x32_bf16 v[34:37], v[154:157], v[170:173], 0
	v_mfma_f32_16x16x32_bf16 v[22:25], v[146:149], v[208:211], 0
	v_mfma_f32_16x16x32_bf16 v[18:21], v[154:157], v[208:211], 0
	v_mfma_f32_16x16x32_bf16 v[6:9], v[146:149], v[218:221], 0
	v_mfma_f32_16x16x32_bf16 v[2:5], v[154:157], v[218:221], 0
	v_mfma_f32_16x16x32_bf16 v[54:57], v[150:153], v[166:169], v[54:57]
	v_mfma_f32_16x16x32_bf16 v[50:53], v[158:161], v[166:169], v[50:53]
	v_mfma_f32_16x16x32_bf16 v[38:41], v[150:153], v[174:177], v[38:41]
	v_mfma_f32_16x16x32_bf16 v[34:37], v[158:161], v[174:177], v[34:37]
	v_mfma_f32_16x16x32_bf16 v[22:25], v[150:153], v[214:217], v[22:25]
	v_mfma_f32_16x16x32_bf16 v[18:21], v[158:161], v[214:217], v[18:21]
	v_mfma_f32_16x16x32_bf16 v[6:9], v[150:153], v[222:225], v[6:9]
	v_mfma_f32_16x16x32_bf16 v[2:5], v[158:161], v[222:225], v[2:5]
	s_setprio 0
	s_barrier
	s_branch .Lpeel_mid_464

; #define PG8_STAGE(bufoff, gbase, voff) do { _Pragma("unroll") for (int _i = 0; _i < 2; ++_i) \
;         __builtin_amdgcn_global_load_lds((const unsigned*)((const char*)(gbase) + (voff)[_i]), (PG8_LAS unsigned*)(lds + (bufoff) + ldsw + _i * 8192), 16, 0, 0); } while (0)
; #define PG8_LDA(dst, b, h) do { _Pragma("unroll") for (int m = 0; m < 4; ++m) _Pragma("unroll") for (int k = 0; k < 2; ++k) dst[m][k] = *(const PG8_LAS bf16x8*)(lds + PG8_SA(b, h) + aoff + m * 2048 + k * 1024); } while (0)
; #define PG8_LDB(dst, b, h) do { _Pragma("unroll") for (int n = 0; n < 2; ++n) _Pragma("unroll") for (int k = 0; k < 2; ++k) dst[n][k] = *(const PG8_LAS bf16x8*)(lds + PG8_SB(b, h) + boff + n * 2048 + k * 1024); } while (0)
; #define PG8_MMA(ai, bj, At, Bt) do { __builtin_amdgcn_s_setprio(1); _Pragma("unroll") for (int m = 0; m < 4; ++m) _Pragma("unroll") for (int n = 0; n < 2; ++n) _Pragma("unroll") for (int k = 0; k < 2; ++k) \
;         acc[ai][bj][m][n] = __builtin_amdgcn_mfma_f32_16x16x32_bf16(Bt[n][k], At[m][k], acc[ai][bj][m][n], 0, 0, 0); __builtin_amdgcn_s_setprio(0); } while (0)
; #define PG8_WAIT_V(n) asm volatile("s_waitcnt vmcnt(" #n ")" ::: "memory")
; #define PG8_WAIT_L(n) asm volatile("s_waitcnt lgkmcnt(" #n ")" ::: "memory")
; #define PG8_BAR __builtin_amdgcn_s_barrier()
; #define PG8_SCHED __builtin_amdgcn_sched_barrier(0)
; template <class Epi, class Sched>
; __device__ __forceinline__ void gemm_phase(PG8_LAS unsigned char* lds, const Gemm g, const Sched& S, const Epi& E) {
;     ...
;         const bool has_next = S.next(ui + 1, nxt);
;         const char* nA = has_next ? (const char*)g.A + (size_t)nxt.pm * tstepA : cA; const char* nB = has_next ? (const char*)g.Bt + (size_t)nxt.pn * tstepB : cB;
;         for (int t = 0; t < nt; t += 2) {
;             const bool last = (t == nt - 2);
;             const char* a1 = cA + (size_t)(t + 1) * kstep;
;             const char* a2 = last ? nA : cA + (size_t)(t + 2) * kstep; const char* b2 = last ? nB : cB + (size_t)(t + 2) * kstep;
;             const char* a3 = a2 + kstep; const char* b3 = b2 + kstep;
;             PG8_LDB(B0, 0, 0); PG8_LDB(B1, 0, 1); PG8_SCHED; PG8_LDA(At, 0, 0); PG8_STAGE(PG8_SA(1, 1), a1 + hstepA, voffA);
;             PG8_WAIT_V(8); PG8_WAIT_L(0); PG8_BAR; PG8_MMA(0, 0, At, B0); PG8_MMA(0, 1, At, B1); PG8_BAR; PG8_SCHED;
.LBB0_580:
	s_ashr_i32 s11, s10, 31
	s_lshl_b64 s[16:17], s[10:11], 19
	s_add_u32 s16, s36, s16
	s_addc_u32 s17, s37, s17
	s_and_b64 s[18:19], s[20:21], exec
	s_cselect_b32 s33, s17, s23
	s_cselect_b32 s46, s16, s22
	s_ashr_i32 s15, s14, 31
	s_lshl_b64 s[18:19], s[14:15], 19
	s_add_u32 s18, s29, s18
	s_addc_u32 s19, s30, s19
	s_and_b64 s[26:27], s[20:21], exec
	s_cselect_b32 s15, s19, s25
	s_cselect_b32 s47, s18, s24
	s_add_u32 s22, s22, 0x40080
	s_addc_u32 s23, s23, 0
	s_add_u32 s48, s24, 0x100
	v_mov_b32_e32 v2, 0
	s_addc_u32 s49, s25, 0
	s_mov_b32 s57, -2
	s_add_u32 s24, s22, 0xfffc0080
	s_addc_u32 s25, s23, -1
	s_add_i32 s58, 0, 0x10000
	s_cmp_eq_u32 s57, 12
	s_cselect_b32 s27, s33, s25
	s_cselect_b32 s26, s46, s24
	v_add_u32_e32 v148, s58, v150
	s_cselect_b32 s25, s15, s49
	s_cselect_b32 s24, s47, s48
	s_add_i32 s64, 0, 0x14000
	ds_read_b128 v[98:101], v148
	ds_read_b128 v[156:159], v148 offset:1024
	ds_read_b128 v[160:163], v148 offset:2048
	ds_read_b128 v[164:167], v148 offset:3072
	v_add_u32_e32 v148, s64, v150
	ds_read_b128 v[168:171], v148
	ds_read_b128 v[172:175], v148 offset:1024
	ds_read_b128 v[176:179], v148 offset:2048
	ds_read_b128 v[180:183], v148 offset:3072
	v_lshl_add_u64 v[148:149], s[22:23], 0, v[144:145]
	s_add_i32 m0, s31, 0xc000
	ds_read_b128 v[184:187], v154
	ds_read_b128 v[188:191], v154 offset:1024
	ds_read_b128 v[192:195], v154 offset:2048
	ds_read_b128 v[196:199], v154 offset:3072
	ds_read_b128 v[200:203], v154 offset:4096
	ds_read_b128 v[204:207], v154 offset:5120
	ds_read_b128 v[208:211], v154 offset:6144
	ds_read_b128 v[214:217], v154 offset:7168
	global_load_lds_dwordx4 v[148:149], off
	v_lshl_add_u64 v[148:149], s[22:23], 0, v[146:147]
	s_add_i32 m0, s31, 0xe000
	s_nop 0
	global_load_lds_dwordx4 v[148:149], off
	s_waitcnt vmcnt(16)
	s_waitcnt lgkmcnt(0)
	s_barrier
	s_setprio 1
	s_waitcnt lgkmcnt(0)
	v_mfma_f32_16x16x32_bf16 v[130:133], v[98:101], v[184:187], 0
	v_mfma_f32_16x16x32_bf16 v[126:129], v[160:163], v[184:187], 0
	v_mfma_f32_16x16x32_bf16 v[114:117], v[98:101], v[192:195], 0
	v_mfma_f32_16x16x32_bf16 v[110:113], v[160:163], v[192:195], 0
	v_mfma_f32_16x16x32_bf16 v[94:97], v[98:101], v[200:203], 0
	v_mfma_f32_16x16x32_bf16 v[90:93], v[160:163], v[200:203], 0
	v_mfma_f32_16x16x32_bf16 v[78:81], v[98:101], v[208:211], 0
	v_mfma_f32_16x16x32_bf16 v[74:77], v[160:163], v[208:211], 0
	v_mfma_f32_16x16x32_bf16 v[130:133], v[156:159], v[188:191], v[130:133]
	v_mfma_f32_16x16x32_bf16 v[126:129], v[164:167], v[188:191], v[126:129]
	v_mfma_f32_16x16x32_bf16 v[114:117], v[156:159], v[196:199], v[114:117]
	v_mfma_f32_16x16x32_bf16 v[110:113], v[164:167], v[196:199], v[110:113]
	v_mfma_f32_16x16x32_bf16 v[94:97], v[156:159], v[204:207], v[94:97]
	v_mfma_f32_16x16x32_bf16 v[90:93], v[164:167], v[204:207], v[90:93]
	v_mfma_f32_16x16x32_bf16 v[78:81], v[156:159], v[214:217], v[78:81]
	v_mfma_f32_16x16x32_bf16 v[74:77], v[164:167], v[214:217], v[74:77]
	s_setprio 0
	s_setprio 1
	v_mfma_f32_16x16x32_bf16 v[122:125], v[168:171], v[184:187], 0
	v_mfma_f32_16x16x32_bf16 v[118:121], v[176:179], v[184:187], 0
	v_mfma_f32_16x16x32_bf16 v[106:109], v[168:171], v[192:195], 0
	v_mfma_f32_16x16x32_bf16 v[102:105], v[176:179], v[192:195], 0
	v_mfma_f32_16x16x32_bf16 v[86:89], v[168:171], v[200:203], 0
	v_mfma_f32_16x16x32_bf16 v[82:85], v[176:179], v[200:203], 0
	v_mfma_f32_16x16x32_bf16 v[70:73], v[168:171], v[208:211], 0
	v_mfma_f32_16x16x32_bf16 v[66:69], v[176:179], v[208:211], 0
	v_mfma_f32_16x16x32_bf16 v[122:125], v[172:175], v[188:191], v[122:125]
	v_mfma_f32_16x16x32_bf16 v[118:121], v[180:183], v[188:191], v[118:121]
	v_mfma_f32_16x16x32_bf16 v[106:109], v[172:175], v[196:199], v[106:109]
	v_mfma_f32_16x16x32_bf16 v[102:105], v[180:183], v[196:199], v[102:105]
	v_mfma_f32_16x16x32_bf16 v[86:89], v[172:175], v[204:207], v[86:89]
	v_mfma_f32_16x16x32_bf16 v[82:85], v[180:183], v[204:207], v[82:85]
	v_mfma_f32_16x16x32_bf16 v[70:73], v[172:175], v[214:217], v[70:73]
	v_mfma_f32_16x16x32_bf16 v[66:69], v[180:183], v[214:217], v[66:69]
	s_setprio 0
	s_barrier
; #define PG8_STAGE(bufoff, gbase, voff) do { _Pragma("unroll") for (int _i = 0; _i < 2; ++_i) \
;         __builtin_amdgcn_global_load_lds((const unsigned*)((const char*)(gbase) + (voff)[_i]), (PG8_LAS unsigned*)(lds + (bufoff) + ldsw + _i * 8192), 16, 0, 0); } while (0)
; #define PG8_LDA(dst, b, h) do { _Pragma("unroll") for (int m = 0; m < 4; ++m) _Pragma("unroll") for (int k = 0; k < 2; ++k) dst[m][k] = *(const PG8_LAS bf16x8*)(lds + PG8_SA(b, h) + aoff + m * 2048 + k * 1024); } while (0)
; #define PG8_MMA(ai, bj, At, Bt) do { __builtin_amdgcn_s_setprio(1); _Pragma("unroll") for (int m = 0; m < 4; ++m) _Pragma("unroll") for (int n = 0; n < 2; ++n) _Pragma("unroll") for (int k = 0; k < 2; ++k) \
;         acc[ai][bj][m][n] = __builtin_amdgcn_mfma_f32_16x16x32_bf16(Bt[n][k], At[m][k], acc[ai][bj][m][n], 0, 0, 0); __builtin_amdgcn_s_setprio(0); } while (0)
; #define PG8_WAIT_V(n) asm volatile("s_waitcnt vmcnt(" #n ")" ::: "memory")
; #define PG8_WAIT_L(n) asm volatile("s_waitcnt lgkmcnt(" #n ")" ::: "memory")
; #define PG8_BAR __builtin_amdgcn_s_barrier()
; #define PG8_SCHED __builtin_amdgcn_sched_barrier(0)
; template <class Epi, class Sched>
; __device__ __forceinline__ void gemm_phase(PG8_LAS unsigned char* lds, const Gemm g, const Sched& S, const Epi& E) {
;     ...
;             PG8_LDA(At, 0, 1); PG8_STAGE(PG8_SB(0, 0), b2, voffB); PG8_STAGE(PG8_SB(0, 1), b2 + hstepB, voffB); PG8_STAGE(PG8_SA(0, 0), a2, voffA);
;             PG8_WAIT_V(8); PG8_WAIT_L(0); PG8_BAR; PG8_MMA(1, 0, At, B0); PG8_MMA(1, 1, At, B1); PG8_BAR; PG8_SCHED;
	s_add_i32 s58, s58, s28
	v_lshl_add_u64 v[148:149], s[24:25], 0, v[136:137]
	s_mov_b32 m0, s58
	ds_read_b128 v[184:187], v154 offset:16384
	ds_read_b128 v[188:191], v154 offset:17408
	ds_read_b128 v[192:195], v154 offset:18432
	ds_read_b128 v[196:199], v154 offset:19456
	ds_read_b128 v[200:203], v154 offset:20480
	ds_read_b128 v[204:207], v154 offset:21504
	ds_read_b128 v[208:211], v154 offset:22528
	ds_read_b128 v[214:217], v154 offset:23552
	global_load_lds_dwordx4 v[148:149], off
	s_add_i32 m0, s58, 0x2000
	s_add_u32 s58, s24, 0x40000
	v_lshl_add_u64 v[212:213], s[24:25], 0, v[140:141]
	s_addc_u32 s59, s25, 0
	s_add_i32 s64, s64, s28
	global_load_lds_dwordx4 v[212:213], off
	v_lshl_add_u64 v[218:219], s[58:59], 0, v[136:137]
	s_mov_b32 m0, s64
	v_lshl_add_u64 v[220:221], s[26:27], 0, v[138:139]
	global_load_lds_dwordx4 v[218:219], off
	v_lshl_add_u64 v[218:219], s[58:59], 0, v[140:141]
	s_add_i32 m0, s64, 0x2000
	s_nop 0
	global_load_lds_dwordx4 v[218:219], off
	v_lshl_add_u64 v[218:219], s[26:27], 0, v[134:135]
	s_mov_b32 m0, s31
	s_nop 0
	global_load_lds_dwordx4 v[218:219], off
	s_mov_b32 m0, s60
	s_nop 0
	global_load_lds_dwordx4 v[220:221], off
	s_waitcnt vmcnt(8)
	s_waitcnt lgkmcnt(0)
	s_barrier
	s_setprio 1
	s_waitcnt lgkmcnt(0)
	v_mfma_f32_16x16x32_bf16 v[62:65], v[98:101], v[184:187], 0
	v_mfma_f32_16x16x32_bf16 v[58:61], v[160:163], v[184:187], 0
	v_mfma_f32_16x16x32_bf16 v[46:49], v[98:101], v[192:195], 0
	v_mfma_f32_16x16x32_bf16 v[42:45], v[160:163], v[192:195], 0
	v_mfma_f32_16x16x32_bf16 v[30:33], v[98:101], v[200:203], 0
	v_mfma_f32_16x16x32_bf16 v[26:29], v[160:163], v[200:203], 0
	v_mfma_f32_16x16x32_bf16 v[14:17], v[98:101], v[208:211], 0
	v_mfma_f32_16x16x32_bf16 v[10:13], v[160:163], v[208:211], 0
	v_mfma_f32_16x16x32_bf16 v[62:65], v[156:159], v[188:191], v[62:65]
	v_mfma_f32_16x16x32_bf16 v[58:61], v[164:167], v[188:191], v[58:61]
	v_mfma_f32_16x16x32_bf16 v[46:49], v[156:159], v[196:199], v[46:49]
	v_mfma_f32_16x16x32_bf16 v[42:45], v[164:167], v[196:199], v[42:45]
	v_mfma_f32_16x16x32_bf16 v[30:33], v[156:159], v[204:207], v[30:33]
	v_mfma_f32_16x16x32_bf16 v[26:29], v[164:167], v[204:207], v[26:29]
	v_mfma_f32_16x16x32_bf16 v[14:17], v[156:159], v[214:217], v[14:17]
	v_mfma_f32_16x16x32_bf16 v[10:13], v[164:167], v[214:217], v[10:13]
	s_setprio 0
	s_setprio 1
	v_mfma_f32_16x16x32_bf16 v[54:57], v[168:171], v[184:187], 0
	v_mfma_f32_16x16x32_bf16 v[50:53], v[176:179], v[184:187], 0
	v_mfma_f32_16x16x32_bf16 v[38:41], v[168:171], v[192:195], 0
	v_mfma_f32_16x16x32_bf16 v[34:37], v[176:179], v[192:195], 0
	v_mfma_f32_16x16x32_bf16 v[22:25], v[168:171], v[200:203], 0
	v_mfma_f32_16x16x32_bf16 v[18:21], v[176:179], v[200:203], 0
	v_mfma_f32_16x16x32_bf16 v[6:9], v[168:171], v[208:211], 0
	v_mfma_f32_16x16x32_bf16 v[2:5], v[176:179], v[208:211], 0
	v_mfma_f32_16x16x32_bf16 v[54:57], v[172:175], v[188:191], v[54:57]
	v_mfma_f32_16x16x32_bf16 v[50:53], v[180:183], v[188:191], v[50:53]
	v_mfma_f32_16x16x32_bf16 v[38:41], v[172:175], v[196:199], v[38:41]
	v_mfma_f32_16x16x32_bf16 v[34:37], v[180:183], v[196:199], v[34:37]
	v_mfma_f32_16x16x32_bf16 v[22:25], v[172:175], v[204:207], v[22:25]
	v_mfma_f32_16x16x32_bf16 v[18:21], v[180:183], v[204:207], v[18:21]
	v_mfma_f32_16x16x32_bf16 v[6:9], v[172:175], v[214:217], v[6:9]
	v_mfma_f32_16x16x32_bf16 v[2:5], v[180:183], v[214:217], v[2:5]
	s_setprio 0
	s_barrier
	s_branch .Lpeel_mid_581

; #define PG8_STAGE(bufoff, gbase, voff) do { _Pragma("unroll") for (int _i = 0; _i < 2; ++_i) \
;         __builtin_amdgcn_global_load_lds((const unsigned*)((const char*)(gbase) + (voff)[_i]), (PG8_LAS unsigned*)(lds + (bufoff) + ldsw + _i * 8192), 16, 0, 0); } while (0)
; #define PG8_LDA(dst, b, h) do { _Pragma("unroll") for (int m = 0; m < 4; ++m) _Pragma("unroll") for (int k = 0; k < 2; ++k) dst[m][k] = *(const PG8_LAS bf16x8*)(lds + PG8_SA(b, h) + aoff + m * 2048 + k * 1024); } while (0)
; #define PG8_LDB(dst, b, h) do { _Pragma("unroll") for (int n = 0; n < 2; ++n) _Pragma("unroll") for (int k = 0; k < 2; ++k) dst[n][k] = *(const PG8_LAS bf16x8*)(lds + PG8_SB(b, h) + boff + n * 2048 + k * 1024); } while (0)
; #define PG8_MMA(ai, bj, At, Bt) do { __builtin_amdgcn_s_setprio(1); _Pragma("unroll") for (int m = 0; m < 4; ++m) _Pragma("unroll") for (int n = 0; n < 2; ++n) _Pragma("unroll") for (int k = 0; k < 2; ++k) \
;         acc[ai][bj][m][n] = __builtin_amdgcn_mfma_f32_16x16x32_bf16(Bt[n][k], At[m][k], acc[ai][bj][m][n], 0, 0, 0); __builtin_amdgcn_s_setprio(0); } while (0)
; #define PG8_WAIT_V(n) asm volatile("s_waitcnt vmcnt(" #n ")" ::: "memory")
; #define PG8_WAIT_L(n) asm volatile("s_waitcnt lgkmcnt(" #n ")" ::: "memory")
; #define PG8_BAR __builtin_amdgcn_s_barrier()
; #define PG8_SCHED __builtin_amdgcn_sched_barrier(0)
; template <class Epi, class Sched>
; __device__ __forceinline__ void gemm_phase(PG8_LAS unsigned char* lds, const Gemm g, const Sched& S, const Epi& E) {
;     ...
;             const char* a2 = last ? nA : cA + (size_t)(t + 2) * kstep; const char* b2 = last ? nB : cB + (size_t)(t + 2) * kstep;
;             const char* a3 = a2 + kstep; const char* b3 = b2 + kstep;
;             PG8_LDB(B0, 0, 0); PG8_LDB(B1, 0, 1); PG8_SCHED; PG8_LDA(At, 0, 0); PG8_STAGE(PG8_SA(1, 1), a1 + hstepA, voffA);
;             PG8_WAIT_V(8); PG8_WAIT_L(0); PG8_BAR; PG8_MMA(0, 0, At, B0); PG8_MMA(0, 1, At, B1); PG8_BAR; PG8_SCHED;
;             PG8_LDA(At, 0, 1); PG8_STAGE(PG8_SB(0, 0), b2, voffB); PG8_STAGE(PG8_SB(0, 1), b2 + hstepB, voffB); PG8_STAGE(PG8_SA(0, 0), a2, voffA);
;             PG8_WAIT_V(8); PG8_WAIT_L(0); PG8_BAR; PG8_MMA(1, 0, At, B0); PG8_MMA(1, 1, At, B1); PG8_BAR; PG8_SCHED;
.LBB0_666:
	s_add_u32 s19, s28, 0x100
	v_mov_b32_e32 v2, 0
	s_addc_u32 s25, s29, 0
	s_mov_b32 s33, -2
	s_add_u32 s10, s26, 0x100
	s_addc_u32 s11, s27, 0
	s_add_i32 s46, 0, 0x10000
	s_cmp_eq_u32 s33, 40
	s_cselect_b32 s31, s21, s11
	s_cselect_b32 s30, s20, s10
	s_cselect_b32 s29, s23, s25
	s_cselect_b32 s28, s22, s19
	s_add_i32 s47, 0, 0x14000
	v_add_u32_e32 v106, s46, v1
	v_add_u32_e32 v158, s47, v1
	ds_read_b128 v[90:93], v106
	ds_read_b128 v[94:97], v106 offset:1024
	ds_read_b128 v[98:101], v106 offset:2048
	ds_read_b128 v[106:109], v106 offset:3072
	ds_read_b128 v[146:149], v158
	ds_read_b128 v[150:153], v158 offset:1024
	ds_read_b128 v[154:157], v158 offset:2048
	ds_read_b128 v[158:161], v158 offset:3072
	v_lshl_add_u64 v[212:213], s[26:27], 0, v[204:205]
	s_add_i32 m0, s61, 0xc000
	ds_read_b128 v[162:165], v232
	ds_read_b128 v[166:169], v232 offset:1024
	ds_read_b128 v[170:173], v232 offset:2048
	ds_read_b128 v[174:177], v232 offset:3072
	ds_read_b128 v[208:211], v232 offset:4096
	ds_read_b128 v[214:217], v232 offset:5120
	ds_read_b128 v[218:221], v232 offset:6144
	ds_read_b128 v[222:225], v232 offset:7168
	global_load_lds_dwordx4 v[212:213], off
	v_lshl_add_u64 v[212:213], s[26:27], 0, v[206:207]
	s_add_i32 m0, s61, 0xe000
	s_nop 0
	global_load_lds_dwordx4 v[212:213], off
	s_waitcnt vmcnt(16)
	s_waitcnt lgkmcnt(0)
	s_barrier
	s_setprio 1
	s_waitcnt lgkmcnt(0)
	v_mfma_f32_16x16x32_bf16 v[142:145], v[90:93], v[162:165], 0
	v_mfma_f32_16x16x32_bf16 v[138:141], v[98:101], v[162:165], 0
	v_mfma_f32_16x16x32_bf16 v[126:129], v[90:93], v[170:173], 0
	v_mfma_f32_16x16x32_bf16 v[122:125], v[98:101], v[170:173], 0
	v_mfma_f32_16x16x32_bf16 v[110:113], v[90:93], v[208:211], 0
	v_mfma_f32_16x16x32_bf16 v[102:105], v[98:101], v[208:211], 0
	v_mfma_f32_16x16x32_bf16 v[78:81], v[90:93], v[218:221], 0
	v_mfma_f32_16x16x32_bf16 v[74:77], v[98:101], v[218:221], 0
	v_mfma_f32_16x16x32_bf16 v[142:145], v[94:97], v[166:169], v[142:145]
	v_mfma_f32_16x16x32_bf16 v[138:141], v[106:109], v[166:169], v[138:141]
	v_mfma_f32_16x16x32_bf16 v[126:129], v[94:97], v[174:177], v[126:129]
	v_mfma_f32_16x16x32_bf16 v[122:125], v[106:109], v[174:177], v[122:125]
	v_mfma_f32_16x16x32_bf16 v[110:113], v[94:97], v[214:217], v[110:113]
	v_mfma_f32_16x16x32_bf16 v[102:105], v[106:109], v[214:217], v[102:105]
	v_mfma_f32_16x16x32_bf16 v[78:81], v[94:97], v[222:225], v[78:81]
	v_mfma_f32_16x16x32_bf16 v[74:77], v[106:109], v[222:225], v[74:77]
	s_setprio 0
	s_setprio 1
	v_mfma_f32_16x16x32_bf16 v[134:137], v[146:149], v[162:165], 0
	v_mfma_f32_16x16x32_bf16 v[130:133], v[154:157], v[162:165], 0
	v_mfma_f32_16x16x32_bf16 v[118:121], v[146:149], v[170:173], 0
	v_mfma_f32_16x16x32_bf16 v[114:117], v[154:157], v[170:173], 0
	v_mfma_f32_16x16x32_bf16 v[86:89], v[146:149], v[208:211], 0
	v_mfma_f32_16x16x32_bf16 v[82:85], v[154:157], v[208:211], 0
	v_mfma_f32_16x16x32_bf16 v[70:73], v[146:149], v[218:221], 0
	v_mfma_f32_16x16x32_bf16 v[66:69], v[154:157], v[218:221], 0
	v_mfma_f32_16x16x32_bf16 v[134:137], v[150:153], v[166:169], v[134:137]
	v_mfma_f32_16x16x32_bf16 v[130:133], v[158:161], v[166:169], v[130:133]
	v_mfma_f32_16x16x32_bf16 v[118:121], v[150:153], v[174:177], v[118:121]
	v_mfma_f32_16x16x32_bf16 v[114:117], v[158:161], v[174:177], v[114:117]
	v_mfma_f32_16x16x32_bf16 v[86:89], v[150:153], v[214:217], v[86:89]
	v_mfma_f32_16x16x32_bf16 v[82:85], v[158:161], v[214:217], v[82:85]
	v_mfma_f32_16x16x32_bf16 v[70:73], v[150:153], v[222:225], v[70:73]
	v_mfma_f32_16x16x32_bf16 v[66:69], v[158:161], v[222:225], v[66:69]
	s_setprio 0
	s_barrier
	s_add_i32 s26, s46, s60
	v_lshl_add_u64 v[212:213], s[28:29], 0, v[182:183]
	s_mov_b32 m0, s26
	ds_read_b128 v[162:165], v232 offset:16384
	ds_read_b128 v[166:169], v232 offset:17408
	ds_read_b128 v[170:173], v232 offset:18432
	ds_read_b128 v[174:177], v232 offset:19456
	ds_read_b128 v[208:211], v232 offset:20480
	ds_read_b128 v[214:217], v232 offset:21504
	ds_read_b128 v[218:221], v232 offset:22528
	ds_read_b128 v[222:225], v232 offset:23552
	global_load_lds_dwordx4 v[212:213], off
	s_add_i32 m0, s26, 0x2000
	s_add_u32 s26, s28, 0xb0000
	v_lshl_add_u64 v[226:227], s[28:29], 0, v[178:179]
	s_addc_u32 s27, s29, 0
	s_add_i32 s46, s47, s60
	global_load_lds_dwordx4 v[226:227], off
	v_lshl_add_u64 v[242:243], s[26:27], 0, v[182:183]
	s_mov_b32 m0, s46
	v_lshl_add_u64 v[246:247], s[30:31], 0, v[180:181]
	global_load_lds_dwordx4 v[242:243], off
	v_lshl_add_u64 v[242:243], s[26:27], 0, v[178:179]
	s_add_i32 m0, s46, 0x2000
	s_nop 0
	global_load_lds_dwordx4 v[242:243], off
	v_lshl_add_u64 v[242:243], s[30:31], 0, v[184:185]
	s_mov_b32 m0, s61
	s_nop 0
	global_load_lds_dwordx4 v[242:243], off
	s_mov_b32 m0, s70
	s_nop 0
	global_load_lds_dwordx4 v[246:247], off
	s_waitcnt vmcnt(8)
	s_waitcnt lgkmcnt(0)
	s_barrier
	s_setprio 1
	s_waitcnt lgkmcnt(0)
	v_mfma_f32_16x16x32_bf16 v[62:65], v[90:93], v[162:165], 0
	v_mfma_f32_16x16x32_bf16 v[58:61], v[98:101], v[162:165], 0
	v_mfma_f32_16x16x32_bf16 v[46:49], v[90:93], v[170:173], 0
	v_mfma_f32_16x16x32_bf16 v[42:45], v[98:101], v[170:173], 0
	v_mfma_f32_16x16x32_bf16 v[30:33], v[90:93], v[208:211], 0
	v_mfma_f32_16x16x32_bf16 v[26:29], v[98:101], v[208:211], 0
	v_mfma_f32_16x16x32_bf16 v[14:17], v[90:93], v[218:221], 0
	v_mfma_f32_16x16x32_bf16 v[10:13], v[98:101], v[218:221], 0
	v_mfma_f32_16x16x32_bf16 v[62:65], v[94:97], v[166:169], v[62:65]
	v_mfma_f32_16x16x32_bf16 v[58:61], v[106:109], v[166:169], v[58:61]
	v_mfma_f32_16x16x32_bf16 v[46:49], v[94:97], v[174:177], v[46:49]
	v_mfma_f32_16x16x32_bf16 v[42:45], v[106:109], v[174:177], v[42:45]
	v_mfma_f32_16x16x32_bf16 v[30:33], v[94:97], v[214:217], v[30:33]
	v_mfma_f32_16x16x32_bf16 v[26:29], v[106:109], v[214:217], v[26:29]
	v_mfma_f32_16x16x32_bf16 v[14:17], v[94:97], v[222:225], v[14:17]
	v_mfma_f32_16x16x32_bf16 v[10:13], v[106:109], v[222:225], v[10:13]
	s_setprio 0
	s_setprio 1
	v_mfma_f32_16x16x32_bf16 v[54:57], v[146:149], v[162:165], 0
	v_mfma_f32_16x16x32_bf16 v[50:53], v[154:157], v[162:165], 0
	v_mfma_f32_16x16x32_bf16 v[38:41], v[146:149], v[170:173], 0
	v_mfma_f32_16x16x32_bf16 v[34:37], v[154:157], v[170:173], 0
	v_mfma_f32_16x16x32_bf16 v[22:25], v[146:149], v[208:211], 0
	v_mfma_f32_16x16x32_bf16 v[18:21], v[154:157], v[208:211], 0
	v_mfma_f32_16x16x32_bf16 v[6:9], v[146:149], v[218:221], 0
	v_mfma_f32_16x16x32_bf16 v[2:5], v[154:157], v[218:221], 0
	v_mfma_f32_16x16x32_bf16 v[54:57], v[150:153], v[166:169], v[54:57]
	v_mfma_f32_16x16x32_bf16 v[50:53], v[158:161], v[166:169], v[50:53]
	v_mfma_f32_16x16x32_bf16 v[38:41], v[150:153], v[174:177], v[38:41]
	v_mfma_f32_16x16x32_bf16 v[34:37], v[158:161], v[174:177], v[34:37]
	v_mfma_f32_16x16x32_bf16 v[22:25], v[150:153], v[214:217], v[22:25]
	v_mfma_f32_16x16x32_bf16 v[18:21], v[158:161], v[214:217], v[18:21]
	v_mfma_f32_16x16x32_bf16 v[6:9], v[150:153], v[222:225], v[6:9]
	v_mfma_f32_16x16x32_bf16 v[2:5], v[158:161], v[222:225], v[2:5]
	s_setprio 0
	s_barrier
	s_branch .Lpeel_mid_667
